# attention softmax: row-max of the second query tile via v_max3 chains (7 fewer VALU per block)
# baseline (speedup 1.0000x reference)
.LBB0_715:
	v_exp_f32_e32 v1, v184
	v_exp_f32_e32 v2, v185
	v_exp_f32_e32 v3, v186
	v_exp_f32_e32 v173, v187
	v_cvt_pk_bf16_f32 v184, v1, v2
	v_cvt_pk_bf16_f32 v185, v3, v173
	v_mov_b32_e32 v1, v0
	v_mov_b32_e32 v2, v0
	v_mov_b32_e32 v3, v0
	v_exp_f32_e32 v187, v190
	v_exp_f32_e32 v174, v188
	v_exp_f32_e32 v175, v189
	v_exp_f32_e32 v188, v191
	v_cvt_pk_bf16_f32 v186, v174, v175
	v_cvt_pk_bf16_f32 v187, v187, v188
	v_max3_f32 v173, v180, v181, v182
	v_mfma_f32_16x16x32_bf16 v[168:171], v[0:3], v[184:187], v[168:171]
	v_max3_f32 v1, v176, v177, v178
	v_max3_f32 v1, v1, v179, v183
	v_max_f32_e32 v1, v1, v173
	s_andn2_b64 vcc, exec, s[78:79]
	s_cbranch_vccnz .LBB0_717
	v_cmp_lt_f32_e32 vcc, s77, v1
	s_cmp_lg_u64 vcc, 0
	s_cselect_b64 s[2:3], -1, 0

.LBB0_721:
	v_exp_f32_e32 v180, v180
	v_exp_f32_e32 v181, v181
	v_exp_f32_e32 v182, v182
	v_exp_f32_e32 v183, v183
	v_exp_f32_e32 v184, v184
	v_exp_f32_e32 v185, v185
	v_exp_f32_e32 v186, v186
	v_exp_f32_e32 v187, v187
	v_cvt_pk_bf16_f32 v180, v180, v181
	v_cvt_pk_bf16_f32 v181, v182, v183
	v_cvt_pk_bf16_f32 v182, v184, v185
	v_cvt_pk_bf16_f32 v183, v186, v187
	v_max3_f32 v184, v172, v173, v174
	v_mfma_f32_16x16x32_bf16 v[168:171], v[0:3], v[180:183], v[168:171]
	v_max3_f32 v1, v176, v177, v178
	v_max3_f32 v1, v1, v179, v175
	v_max_f32_e32 v1, v1, v184
	v_cmp_lt_f32_e32 vcc, s77, v1
	s_cbranch_vccz .LBB0_723
	v_mov_b32_e32 v2, v1
	s_nop 1
	v_permlane16_swap_b32_e32 v1, v2
	v_max_f32_e32 v2, v2, v2
	v_max_f32_e32 v1, v1, v1
	v_max_f32_e32 v1, v1, v2
	v_mov_b32_e32 v2, v1
	s_nop 1
	v_permlane32_swap_b32_e32 v1, v2
	v_max3_f32 v1, v1, v2, 0
	v_exp_f32_e64 v2, -v1
	v_add_f32_e32 v227, v227, v1
	v_sub_f32_e32 v176, v176, v1
	v_sub_f32_e32 v177, v177, v1
	v_pk_mul_f32 v[166:167], v[166:167], v[2:3] op_sel_hi:[1,0]
	v_pk_mul_f32 v[164:165], v[164:165], v[2:3] op_sel_hi:[1,0]
	v_pk_mul_f32 v[158:159], v[158:159], v[2:3] op_sel_hi:[1,0]
	v_pk_mul_f32 v[156:157], v[156:157], v[2:3] op_sel_hi:[1,0]
	v_pk_mul_f32 v[150:151], v[150:151], v[2:3] op_sel_hi:[1,0]
	v_pk_mul_f32 v[148:149], v[148:149], v[2:3] op_sel_hi:[1,0]
	v_pk_mul_f32 v[142:143], v[142:143], v[2:3] op_sel_hi:[1,0]
	v_pk_mul_f32 v[140:141], v[140:141], v[2:3] op_sel_hi:[1,0]
	v_pk_mul_f32 v[134:135], v[134:135], v[2:3] op_sel_hi:[1,0]
	v_pk_mul_f32 v[132:133], v[132:133], v[2:3] op_sel_hi:[1,0]
	v_pk_mul_f32 v[94:95], v[94:95], v[2:3] op_sel_hi:[1,0]
	v_pk_mul_f32 v[92:93], v[92:93], v[2:3] op_sel_hi:[1,0]
	v_pk_mul_f32 v[86:87], v[86:87], v[2:3] op_sel_hi:[1,0]
	v_pk_mul_f32 v[84:85], v[84:85], v[2:3] op_sel_hi:[1,0]
	v_pk_mul_f32 v[78:79], v[78:79], v[2:3] op_sel_hi:[1,0]
	v_pk_mul_f32 v[76:77], v[76:77], v[2:3] op_sel_hi:[1,0]
	v_pk_mul_f32 v[70:71], v[70:71], v[2:3] op_sel_hi:[1,0]
	v_pk_mul_f32 v[68:69], v[68:69], v[2:3] op_sel_hi:[1,0]
	v_pk_mul_f32 v[62:63], v[62:63], v[2:3] op_sel_hi:[1,0]
	v_pk_mul_f32 v[60:61], v[60:61], v[2:3] op_sel_hi:[1,0]
	v_pk_mul_f32 v[54:55], v[54:55], v[2:3] op_sel_hi:[1,0]
	v_pk_mul_f32 v[52:53], v[52:53], v[2:3] op_sel_hi:[1,0]
	v_pk_mul_f32 v[46:47], v[46:47], v[2:3] op_sel_hi:[1,0]
	v_pk_mul_f32 v[44:45], v[44:45], v[2:3] op_sel_hi:[1,0]
	v_pk_mul_f32 v[38:39], v[38:39], v[2:3] op_sel_hi:[1,0]
	v_pk_mul_f32 v[36:37], v[36:37], v[2:3] op_sel_hi:[1,0]
	v_pk_mul_f32 v[30:31], v[30:31], v[2:3] op_sel_hi:[1,0]
	v_pk_mul_f32 v[28:29], v[28:29], v[2:3] op_sel_hi:[1,0]
	v_pk_mul_f32 v[22:23], v[22:23], v[2:3] op_sel_hi:[1,0]
	v_pk_mul_f32 v[20:21], v[20:21], v[2:3] op_sel_hi:[1,0]
	v_pk_mul_f32 v[14:15], v[14:15], v[2:3] op_sel_hi:[1,0]
	v_pk_mul_f32 v[12:13], v[12:13], v[2:3] op_sel_hi:[1,0]
	v_pk_mul_f32 v[6:7], v[6:7], v[2:3] op_sel_hi:[1,0]
	v_pk_mul_f32 v[4:5], v[4:5], v[2:3] op_sel_hi:[1,0]
	v_sub_f32_e32 v178, v178, v1
	v_sub_f32_e32 v179, v179, v1
	v_sub_f32_e32 v172, v172, v1
	v_sub_f32_e32 v173, v173, v1
	v_sub_f32_e32 v174, v174, v1
	v_sub_f32_e32 v175, v175, v1
